# v65 + nt on the prologue's bf16 weight stores
# speedup vs baseline: 1.0010x; 1.0010x over previous
.LBB0_82:
	v_cndmask_b32_e64 v86, 0, 1.0, vcc
	s_waitcnt vmcnt(15)
	v_pk_mul_f32 v[54:55], v[86:87], v[54:55] op_sel_hi:[0,1]
	s_waitcnt vmcnt(14)
	v_pk_mul_f32 v[104:105], v[86:87], v[50:51] op_sel_hi:[0,1]
	s_waitcnt vmcnt(13)
	v_pk_mul_f32 v[62:63], v[86:87], v[62:63] op_sel_hi:[0,1]
	s_waitcnt vmcnt(12)
	v_pk_mul_f32 v[58:59], v[86:87], v[58:59] op_sel_hi:[0,1]
	v_pk_mul_f32 v[102:103], v[86:87], v[52:53] op_sel_hi:[0,1]
	v_mov_b32_e32 v50, v54
	v_mov_b32_e32 v51, v104
	v_mov_b32_e32 v52, v62
	v_mov_b32_e32 v53, v58
	s_waitcnt vmcnt(11)
	v_pk_mul_f32 v[70:71], v[86:87], v[70:71] op_sel_hi:[0,1]
	s_waitcnt vmcnt(10)
	v_pk_mul_f32 v[66:67], v[86:87], v[66:67] op_sel_hi:[0,1]
	s_waitcnt vmcnt(9)
	v_pk_mul_f32 v[78:79], v[86:87], v[78:79] op_sel_hi:[0,1]
	s_waitcnt vmcnt(8)
	v_pk_mul_f32 v[74:75], v[86:87], v[74:75] op_sel_hi:[0,1]
	v_pk_mul_f32 v[50:51], v[50:51], v[14:15]
	v_pk_mul_f32 v[52:53], v[52:53], v[16:17]
	v_cvt_pk_bf16_f32 v50, v50, v51
	v_cvt_pk_bf16_f32 v51, v52, v53
	v_mov_b32_e32 v52, v70
	v_mov_b32_e32 v53, v66
	v_mov_b32_e32 v106, v78
	v_mov_b32_e32 v107, v74
	v_pk_mul_f32 v[52:53], v[52:53], v[10:11]
	v_pk_mul_f32 v[106:107], v[106:107], v[12:13]
	v_or_b32_e32 v54, s65, v85
	s_ashr_i32 s36, s65, 31
	v_cvt_pk_bf16_f32 v52, v52, v53
	v_cvt_pk_bf16_f32 v53, v106, v107
	v_mul_lo_u32 v58, s27, v54
	s_mul_i32 s40, s26, s36
	v_mad_u64_u32 v[106:107], s[36:37], s26, v54, 0
	v_add3_u32 v107, v107, s40, v58
	v_lshl_add_u64 v[106:107], v[106:107], 1, s[22:23]
	s_lshl_b64 s[24:25], s[24:25], 1
	v_pk_mul_f32 v[56:57], v[86:87], v[56:57] op_sel_hi:[0,1]
	v_pk_mul_f32 v[64:65], v[86:87], v[64:65] op_sel_hi:[0,1]
	v_pk_mul_f32 v[60:61], v[86:87], v[60:61] op_sel_hi:[0,1]
	v_pk_mul_f32 v[72:73], v[86:87], v[72:73] op_sel_hi:[0,1]
	v_pk_mul_f32 v[68:69], v[86:87], v[68:69] op_sel_hi:[0,1]
	v_pk_mul_f32 v[80:81], v[86:87], v[80:81] op_sel_hi:[0,1]
	v_pk_mul_f32 v[76:77], v[86:87], v[76:77] op_sel_hi:[0,1]
	v_lshl_add_u64 v[106:107], v[106:107], 0, s[24:25]
	v_lshlrev_b32_e32 v86, 1, v84
	v_lshl_add_u64 v[106:107], v[106:107], 0, v[86:87]
	v_mov_b32_e32 v104, v55
	v_mov_b32_e32 v58, v63
	global_store_dwordx4 v[106:107], v[50:53], off nt
	v_mov_b32_e32 v66, v71
	v_mov_b32_e32 v74, v79
	v_pk_mul_f32 v[50:51], v[104:105], v[14:15]
	v_pk_mul_f32 v[52:53], v[58:59], v[16:17]
	v_cvt_pk_bf16_f32 v50, v50, v51
	v_cvt_pk_bf16_f32 v51, v52, v53
	v_pk_mul_f32 v[52:53], v[66:67], v[10:11]
	v_pk_mul_f32 v[54:55], v[74:75], v[12:13]
	v_cvt_pk_bf16_f32 v52, v52, v53
	v_cvt_pk_bf16_f32 v53, v54, v55
	v_or_b32_e32 v54, s65, v97
	v_mul_lo_u32 v58, s27, v54
	v_mad_u64_u32 v[54:55], s[36:37], s26, v54, 0
	v_add3_u32 v55, v55, s40, v58
	v_lshl_add_u64 v[54:55], v[54:55], 1, s[22:23]
	v_lshl_add_u64 v[54:55], v[54:55], 0, s[24:25]
	v_lshl_add_u64 v[54:55], v[54:55], 0, v[86:87]
	global_store_dwordx4 v[54:55], v[50:53], off nt
	v_mov_b32_e32 v54, v80
	v_mov_b32_e32 v55, v76
	v_mov_b32_e32 v50, v56
	v_mov_b32_e32 v51, v102
	v_mov_b32_e32 v52, v64
	v_mov_b32_e32 v53, v60
	v_pk_mul_f32 v[50:51], v[50:51], v[14:15]
	v_pk_mul_f32 v[52:53], v[52:53], v[16:17]
	v_cvt_pk_bf16_f32 v50, v50, v51
	v_cvt_pk_bf16_f32 v51, v52, v53
	v_mov_b32_e32 v52, v72
	v_mov_b32_e32 v53, v68
	v_mov_b32_e32 v102, v57
	v_mov_b32_e32 v60, v65
	v_mov_b32_e32 v68, v73
	v_pk_mul_f32 v[52:53], v[52:53], v[10:11]
	v_pk_mul_f32 v[14:15], v[102:103], v[14:15]
	v_pk_mul_f32 v[16:17], v[60:61], v[16:17]
	v_pk_mul_f32 v[10:11], v[68:69], v[10:11]
	v_mov_b32_e32 v76, v81
	v_pk_mul_f32 v[54:55], v[54:55], v[12:13]
	v_cvt_pk_bf16_f32 v14, v14, v15
	v_cvt_pk_bf16_f32 v15, v16, v17
	v_cvt_pk_bf16_f32 v16, v10, v11
	v_pk_mul_f32 v[10:11], v[76:77], v[12:13]
	v_cvt_pk_bf16_f32 v52, v52, v53
	v_cvt_pk_bf16_f32 v53, v54, v55
	v_or_b32_e32 v54, s65, v98
	v_cvt_pk_bf16_f32 v17, v10, v11
	v_or_b32_e32 v10, s65, v99
	v_mul_lo_u32 v56, s27, v54
	v_mad_u64_u32 v[54:55], s[36:37], s26, v54, 0
	v_mul_lo_u32 v12, s27, v10
	v_mad_u64_u32 v[10:11], s[26:27], s26, v10, 0
	v_add3_u32 v55, v55, s40, v56
	v_add3_u32 v11, v11, s40, v12
	v_lshl_add_u64 v[54:55], v[54:55], 1, s[22:23]
	v_lshl_add_u64 v[10:11], v[10:11], 1, s[22:23]
	v_lshl_add_u64 v[54:55], v[54:55], 0, s[24:25]
	v_lshl_add_u64 v[10:11], v[10:11], 0, s[24:25]
	v_lshl_add_u64 v[54:55], v[54:55], 0, v[86:87]
	v_lshl_add_u64 v[10:11], v[10:11], 0, v[86:87]
	s_andn2_b64 vcc, exec, s[28:29]
	global_store_dwordx4 v[54:55], v[50:53], off nt
	global_store_dwordx4 v[10:11], v[14:17], off nt
	s_cbranch_vccnz .LBB0_16
	v_cndmask_b32_e64 v10, 0, 1.0, s[4:5]
	s_waitcnt vmcnt(11)
	v_pk_mul_f32 v[14:15], v[10:11], v[24:25] op_sel_hi:[0,1]
	v_pk_mul_f32 v[16:17], v[10:11], v[22:23] op_sel_hi:[0,1]
	s_waitcnt vmcnt(10)
	v_pk_mul_f32 v[18:19], v[10:11], v[18:19] op_sel_hi:[0,1]
	s_waitcnt vmcnt(9)
	v_pk_mul_f32 v[24:25], v[10:11], v[30:31] op_sel_hi:[0,1]
	s_waitcnt vmcnt(8)
	v_pk_mul_f32 v[26:27], v[10:11], v[26:27] op_sel_hi:[0,1]
	v_pk_mul_f32 v[20:21], v[10:11], v[20:21] op_sel_hi:[0,1]
	v_pk_mul_f32 v[22:23], v[10:11], v[32:33] op_sel_hi:[0,1]
	v_pk_mul_f32 v[28:29], v[10:11], v[28:29] op_sel_hi:[0,1]
	s_waitcnt vmcnt(7)
	v_pk_mul_f32 v[30:31], v[10:11], v[40:41] op_sel_hi:[0,1]
	v_pk_mul_f32 v[32:33], v[10:11], v[38:39] op_sel_hi:[0,1]
	s_waitcnt vmcnt(6)
	v_pk_mul_f32 v[36:37], v[10:11], v[36:37] op_sel_hi:[0,1]
	v_pk_mul_f32 v[34:35], v[10:11], v[34:35] op_sel_hi:[0,1]
	s_waitcnt vmcnt(5)
	v_pk_mul_f32 v[38:39], v[10:11], v[48:49] op_sel_hi:[0,1]
	v_pk_mul_f32 v[40:41], v[10:11], v[46:47] op_sel_hi:[0,1]
	s_waitcnt vmcnt(4)
	v_pk_mul_f32 v[44:45], v[10:11], v[44:45] op_sel_hi:[0,1]
	v_pk_mul_f32 v[42:43], v[10:11], v[42:43] op_sel_hi:[0,1]
	v_mov_b32_e32 v10, v16
	v_mov_b32_e32 v11, v18
	v_mov_b32_e32 v12, v24
	v_mov_b32_e32 v13, v26
	v_pk_mul_f32 v[10:11], v[10:11], v[6:7]
	v_pk_mul_f32 v[12:13], v[12:13], v[8:9]
	v_cvt_pk_bf16_f32 v10, v10, v11
	v_cvt_pk_bf16_f32 v11, v12, v13
	v_mov_b32_e32 v12, v32
	v_mov_b32_e32 v13, v34
	v_mov_b32_e32 v46, v40
	v_mov_b32_e32 v47, v42
	v_pk_mul_f32 v[12:13], v[12:13], v[2:3]
	v_pk_mul_f32 v[46:47], v[46:47], v[4:5]
	v_or_b32_e32 v16, s20, v85
	s_ashr_i32 s4, s20, 31
	v_cvt_pk_bf16_f32 v12, v12, v13
	v_cvt_pk_bf16_f32 v13, v46, v47
	v_mul_lo_u32 v18, s39, v16
	s_mul_i32 s24, s38, s4
	v_mad_u64_u32 v[46:47], s[4:5], s38, v16, 0
	v_add3_u32 v47, v47, s24, v18
	v_lshl_add_u64 v[46:47], v[46:47], 1, s[30:31]
	s_lshl_b64 s[4:5], s[34:35], 1
	v_lshl_add_u64 v[46:47], v[46:47], 0, s[4:5]
	v_lshl_add_u64 v[46:47], v[46:47], 0, v[86:87]
	v_mov_b32_e32 v18, v17
	v_mov_b32_e32 v26, v25
	global_store_dwordx4 v[46:47], v[10:13], off nt
	v_mov_b32_e32 v34, v33
	v_mov_b32_e32 v42, v41
	v_pk_mul_f32 v[10:11], v[18:19], v[6:7]
	v_pk_mul_f32 v[12:13], v[26:27], v[8:9]
	v_cvt_pk_bf16_f32 v10, v10, v11
	v_cvt_pk_bf16_f32 v11, v12, v13
	v_pk_mul_f32 v[12:13], v[34:35], v[2:3]
	v_pk_mul_f32 v[16:17], v[42:43], v[4:5]
	v_cvt_pk_bf16_f32 v12, v12, v13
	v_cvt_pk_bf16_f32 v13, v16, v17
	v_or_b32_e32 v16, s20, v97
	v_mul_lo_u32 v18, s39, v16
	v_mad_u64_u32 v[16:17], s[22:23], s38, v16, 0
	v_add3_u32 v17, v17, s24, v18
	v_lshl_add_u64 v[16:17], v[16:17], 1, s[30:31]
	v_lshl_add_u64 v[16:17], v[16:17], 0, s[4:5]
	v_lshl_add_u64 v[16:17], v[16:17], 0, v[86:87]
	global_store_dwordx4 v[16:17], v[10:13], off nt
	v_mov_b32_e32 v17, v44
	v_mov_b32_e32 v44, v39
	v_mov_b32_e32 v10, v14
	v_mov_b32_e32 v11, v20
	v_mov_b32_e32 v12, v22
	v_mov_b32_e32 v13, v28
	v_pk_mul_f32 v[10:11], v[10:11], v[6:7]
	v_pk_mul_f32 v[12:13], v[12:13], v[8:9]
	v_cvt_pk_bf16_f32 v10, v10, v11
	v_cvt_pk_bf16_f32 v11, v12, v13
	v_mov_b32_e32 v12, v30
	v_mov_b32_e32 v13, v36
	v_mov_b32_e32 v20, v15
	v_mov_b32_e32 v28, v23
	v_mov_b32_e32 v36, v31
	v_pk_mul_f32 v[12:13], v[12:13], v[2:3]
	v_pk_mul_f32 v[6:7], v[20:21], v[6:7]
	v_pk_mul_f32 v[8:9], v[28:29], v[8:9]
	v_pk_mul_f32 v[2:3], v[36:37], v[2:3]
	v_mov_b32_e32 v16, v38
	v_cvt_pk_bf16_f32 v6, v6, v7
	v_cvt_pk_bf16_f32 v7, v8, v9
	v_cvt_pk_bf16_f32 v8, v2, v3
	v_pk_mul_f32 v[2:3], v[44:45], v[4:5]
	v_pk_mul_f32 v[16:17], v[16:17], v[4:5]
	v_or_b32_e32 v14, s20, v98
	v_cvt_pk_bf16_f32 v9, v2, v3
	v_or_b32_e32 v2, s20, v99
	v_cvt_pk_bf16_f32 v12, v12, v13
	v_cvt_pk_bf16_f32 v13, v16, v17
	v_mul_lo_u32 v18, s39, v14
	v_mad_u64_u32 v[16:17], s[22:23], s38, v14, 0
	v_mul_lo_u32 v4, s39, v2
	v_mad_u64_u32 v[2:3], s[22:23], s38, v2, 0
	v_add3_u32 v17, v17, s24, v18
	v_add3_u32 v3, v3, s24, v4
	v_lshl_add_u64 v[16:17], v[16:17], 1, s[30:31]
	v_lshl_add_u64 v[2:3], v[2:3], 1, s[30:31]
	v_lshl_add_u64 v[16:17], v[16:17], 0, s[4:5]
	v_lshl_add_u64 v[2:3], v[2:3], 0, s[4:5]
	v_lshl_add_u64 v[16:17], v[16:17], 0, v[86:87]
	v_lshl_add_u64 v[2:3], v[2:3], 0, v[86:87]
	global_store_dwordx4 v[16:17], v[10:13], off nt
	global_store_dwordx4 v[2:3], v[6:9], off nt
	s_branch .LBB0_16
